# v136 plus a warm-up touch of W_out at the end of the mixer stage-3 phase, so every GEMM phase now starts with its bf16 weight in the memory-side cache
# speedup vs baseline: 1.0006x; 1.0006x over previous
.LBB0_623:
	v_lshl_add_u32 v246, s80, 9, v235
	v_and_b32_e32 v246, 0xffff, v246
	v_lshlrev_b32_e32 v246, 7, v246
	v_add_u32_e32 v246, 0x1c00000, v246
	v_mov_b32_e32 v247, 0
	v_lshl_add_u64 v[246:247], s[12:13], 0, v[246:247]
	global_load_dword v250, v[246:247], off
	s_movk_i32 s69, 0x1000
	v_readlane_b32 s48, v255, 17
	s_mov_b64 s[70:71], s[42:43]
	s_mov_b32 s74, s44
	s_mov_b32 s75, s45
	v_readlane_b32 s78, v255, 21
	v_readlane_b32 s49, v255, 18
